# panel-barrier atomic and spin loads (and the cross-panel wait) as global instead of flat operations
# baseline (speedup 1.0000x reference)
.LBB0_210:
	v_mov_b64_e32 v[2:3], s[6:7]
	s_waitcnt vmcnt(0)
	global_load_dword v0, v[2:3], off sc1
	s_or_b64 s[10:11], s[10:11], exec
	s_waitcnt vmcnt(0) lgkmcnt(0)
	v_cmp_gt_u32_e32 vcc, s15, v0
	s_and_saveexec_b64 s[18:19], vcc
	s_cbranch_execz .LBB0_209
	s_cmp_lg_u32 s16, 0
	s_sleep 1
	s_cbranch_scc0 .LBB0_220
	v_mov_b64_e32 v[2:3], s[6:7]
	global_load_dword v0, v[2:3], off sc1
	s_mov_b64 s[22:23], -1
	s_waitcnt vmcnt(0) lgkmcnt(0)
	v_cmp_gt_u32_e32 vcc, s15, v0
	s_and_saveexec_b64 s[20:21], vcc
	s_cbranch_execz .LBB0_207
	v_mov_b64_e32 v[2:3], s[6:7]
	s_sleep 1
	global_load_dword v0, v[2:3], off sc1
	s_mov_b64 s[24:25], -1
	s_waitcnt vmcnt(0) lgkmcnt(0)
	v_cmp_gt_u32_e32 vcc, s15, v0
	s_and_saveexec_b64 s[22:23], vcc
	s_cbranch_execz .LBB0_206
	v_mov_b64_e32 v[2:3], s[6:7]
	s_sleep 1
	global_load_dword v0, v[2:3], off sc1
	s_mov_b64 s[26:27], -1
	s_waitcnt vmcnt(0) lgkmcnt(0)
	v_cmp_gt_u32_e32 vcc, s15, v0
	s_and_saveexec_b64 s[24:25], vcc
	s_cbranch_execz .LBB0_205
	v_mov_b64_e32 v[2:3], s[6:7]
	s_sleep 1
	global_load_dword v0, v[2:3], off sc1
	s_mov_b64 s[28:29], -1
	s_waitcnt vmcnt(0) lgkmcnt(0)
	v_cmp_gt_u32_e32 vcc, s15, v0
	s_and_saveexec_b64 s[26:27], vcc
	s_cbranch_execz .LBB0_204
	v_mov_b64_e32 v[2:3], s[6:7]
	s_sleep 1
	global_load_dword v0, v[2:3], off sc1
	s_mov_b64 s[30:31], -1
	s_waitcnt vmcnt(0) lgkmcnt(0)
	v_cmp_gt_u32_e32 vcc, s15, v0
	s_and_saveexec_b64 s[28:29], vcc
	s_cbranch_execz .LBB0_203
	v_mov_b64_e32 v[2:3], s[6:7]
	s_sleep 1
	global_load_dword v0, v[2:3], off sc1
	s_mov_b64 s[34:35], -1
	s_waitcnt vmcnt(0) lgkmcnt(0)
	v_cmp_gt_u32_e32 vcc, s15, v0
	s_and_saveexec_b64 s[30:31], vcc
	s_cbranch_execz .LBB0_202
	v_mov_b64_e32 v[2:3], s[6:7]
	s_sleep 1
	global_load_dword v0, v[2:3], off sc1
	s_waitcnt vmcnt(0) lgkmcnt(0)
	v_cmp_gt_u32_e32 vcc, s15, v0
	s_and_saveexec_b64 s[36:37], vcc
	s_cbranch_execz .LBB0_201
	s_add_i32 s16, s16, -8
	s_xor_b64 s[34:35], exec, -1
	s_sleep 1
	s_branch .LBB0_201

.LBB0_1136:
	v_readlane_b32 s2, v253, 25
	v_readlane_b32 s3, v253, 26
	s_lshl_b32 s2, s2, 6
	s_ashr_i32 s3, s2, 31
	s_lshl_b64 s[2:3], s[2:3], 2
	s_add_u32 s2, s82, s2
	s_addc_u32 s3, s83, s3
	v_mov_b32_e32 v0, s2
	v_add_co_u32_e32 v2, vcc, 0x8000, v0
	v_mov_b32_e32 v0, s3
	s_nop 0
	v_addc_co_u32_e32 v3, vcc, 0, v0, vcc
	global_atomic_add v[2:3], v220, off
	s_add_u32 s2, s2, 0x8000
	s_addc_u32 s3, s3, 0
	s_lshl_b32 s27, s26, 2
	s_mov_b32 s28, 0x1000000
	s_mov_b64 s[4:5], 0
	s_branch .LBB0_1148

.LBB0_1148:
	v_mov_b64_e32 v[2:3], s[2:3]
	global_load_dword v0, v[2:3], off sc1
	s_or_b64 s[6:7], s[6:7], exec
	s_waitcnt vmcnt(0) lgkmcnt(0)
	v_cmp_gt_u32_e32 vcc, s27, v0
	s_and_saveexec_b64 s[8:9], vcc
	s_cbranch_execz .LBB0_1147
	s_cmp_lg_u32 s28, 0
	s_sleep 1
	s_cbranch_scc0 .LBB0_1158
	v_mov_b64_e32 v[2:3], s[2:3]
	global_load_dword v0, v[2:3], off sc1
	s_mov_b64 s[12:13], -1
	s_waitcnt vmcnt(0) lgkmcnt(0)
	v_cmp_gt_u32_e32 vcc, s27, v0
	s_and_saveexec_b64 s[10:11], vcc
	s_cbranch_execz .LBB0_1145
	v_mov_b64_e32 v[2:3], s[2:3]
	s_sleep 1
	global_load_dword v0, v[2:3], off sc1
	s_mov_b64 s[14:15], -1
	s_waitcnt vmcnt(0) lgkmcnt(0)
	v_cmp_gt_u32_e32 vcc, s27, v0
	s_and_saveexec_b64 s[12:13], vcc
	s_cbranch_execz .LBB0_1144
	v_mov_b64_e32 v[2:3], s[2:3]
	s_sleep 1
	global_load_dword v0, v[2:3], off sc1
	s_mov_b32 s29, s18
	s_mov_b64 s[16:17], -1
	s_waitcnt vmcnt(0) lgkmcnt(0)
	v_cmp_gt_u32_e32 vcc, s27, v0
	s_and_saveexec_b64 s[14:15], vcc
	s_cbranch_execz .LBB0_1143
	v_mov_b64_e32 v[2:3], s[2:3]
	s_sleep 1
	global_load_dword v0, v[2:3], off sc1
	s_mov_b64 s[18:19], -1
	s_waitcnt vmcnt(0) lgkmcnt(0)
	v_cmp_gt_u32_e32 vcc, s27, v0
	s_and_saveexec_b64 s[16:17], vcc
	s_cbranch_execz .LBB0_1142
	v_mov_b64_e32 v[2:3], s[2:3]
	s_sleep 1
	global_load_dword v0, v[2:3], off sc1
	s_mov_b64 s[20:21], -1
	s_waitcnt vmcnt(0) lgkmcnt(0)
	v_cmp_gt_u32_e32 vcc, s27, v0
	s_and_saveexec_b64 s[18:19], vcc
	s_cbranch_execz .LBB0_1141
	v_mov_b64_e32 v[2:3], s[2:3]
	s_sleep 1
	global_load_dword v0, v[2:3], off sc1
	s_mov_b64 s[22:23], -1
	s_waitcnt vmcnt(0) lgkmcnt(0)
	v_cmp_gt_u32_e32 vcc, s27, v0
	s_and_saveexec_b64 s[20:21], vcc
	s_cbranch_execz .LBB0_1140
	v_mov_b64_e32 v[2:3], s[2:3]
	s_sleep 1
	global_load_dword v0, v[2:3], off sc1
	s_waitcnt vmcnt(0) lgkmcnt(0)
	v_cmp_gt_u32_e32 vcc, s27, v0
	s_and_saveexec_b64 s[24:25], vcc
	s_cbranch_execz .LBB0_1139
	s_add_i32 s28, s28, -8
	s_xor_b64 s[22:23], exec, -1
	s_sleep 1
	s_branch .LBB0_1139
